# GEMM phase prologues: K-tile 1's six LDS-DMA pieces issued before the wait for K-tile 0 (wait vmcnt(2)->vmcnt(8)), so both K-tiles' latencies overlap
# baseline (speedup 1.0000x reference)
.LBB0_215:
	s_ashr_i32 s20, s30, 31
	v_bfe_u32 v139, v6, 4, 2
	s_lshr_b32 s20, s20, 26
	v_and_b32_e32 v138, 15, v6
	s_add_i32 s20, s30, s20
	v_lshlrev_b32_e32 v7, 4, v139
	v_lshlrev_b32_e32 v6, 2, v6
	s_ashr_i32 s48, s20, 6
	v_lshl_or_b32 v7, v138, 6, v7
	s_lshl_b32 s20, s35, 13
	v_and_b32_e32 v6, 32, v6
	v_readlane_b32 s82, v254, 33
	v_bitop3_b32 v16, v7, s20, v6 bitop3:0xde
	s_lshl_b32 s20, s31, 5
	v_readlane_b32 s83, v254, 34
	s_and_b32 s55, s20, 0x60
	v_mov_b32_e32 v129, v189
	v_lshl_add_u64 v[8:9], s[82:83], 0, v[188:189]
	v_readlane_b32 s66, v254, 29
	s_lshl_b32 s20, s55, 7
	v_lshl_add_u64 v[10:11], s[82:83], 0, v[128:129]
	v_mov_b32_e32 v133, v189
	v_readlane_b32 s67, v254, 30
	v_bitop3_b32 v140, v7, s20, v6 bitop3:0xde
	s_add_i32 m0, s13, 0x18000
	v_lshl_add_u64 v[6:7], v[8:9], 0, s[62:63]
	v_lshl_add_u64 v[12:13], s[66:67], 0, v[132:133]
	v_mov_b32_e32 v131, v189
	global_load_lds_dwordx4 v[6:7], off
	v_lshl_add_u64 v[6:7], v[10:11], 0, s[62:63]
	s_add_i32 m0, s13, 0x1a000
	s_add_i32 s56, s13, 0x8000
	v_lshl_add_u64 v[14:15], s[66:67], 0, v[130:131]
	global_load_lds_dwordx4 v[6:7], off
	v_lshl_add_u64 v[6:7], v[12:13], 0, s[62:63]
	s_mov_b32 m0, s56
	s_add_i32 s57, s13, 0xa000
	v_readlane_b32 s6, v254, 35
	global_load_lds_dwordx4 v[6:7], off
	v_lshl_add_u64 v[6:7], v[14:15], 0, s[62:63]
	s_mov_b32 m0, s57
	v_readlane_b32 s7, v254, 36
	global_load_lds_dwordx4 v[6:7], off
	s_add_i32 m0, s13, 0x1c000
	v_lshl_add_u64 v[6:7], s[6:7], 0, v[188:189]
	global_load_lds_dwordx4 v[6:7], off
	v_lshl_add_u64 v[6:7], s[6:7], 0, v[128:129]
	s_add_i32 m0, s13, 0x1e000
	s_lshl_b32 s49, s35, 6
	global_load_lds_dwordx4 v[6:7], off
	s_waitcnt vmcnt(8)
	s_barrier
	v_lshlrev_b32_e32 v6, 12, v4
	v_and_b32_e32 v6, 0xffffe000, v6
	v_lshl_add_u32 v3, v3, 9, v6
	v_and_b32_e32 v4, 1, v4
	v_lshl_or_b32 v3, v4, 6, v3
	v_lshl_add_u32 v134, v5, 1, v3
	v_lshlrev_b32_e32 v3, 12, v0
	s_cmp_gt_i32 s30, 63
	v_and_b32_e32 v3, 0xffffe000, v3
	v_readlane_b32 s6, v253, 36
	s_waitcnt vmcnt(6)
	s_cselect_b64 s[30:31], -1, 0
	s_add_i32 s60, s48, -2
	v_lshl_add_u32 v1, v1, 9, v3
	v_and_b32_e32 v0, 1, v0
	v_readlane_b32 s7, v253, 37
	s_cmpk_lt_u32 s34, 0x100
	v_lshl_or_b32 v0, v0, 6, v1
	s_mov_b32 s81, s6
	v_readlane_b32 s6, v254, 11
	s_cselect_b64 s[34:35], -1, 0
	v_mov_b32_e32 v135, v189
	v_lshl_add_u32 v136, v2, 1, v0
	v_mov_b32_e32 v137, v189
	s_mov_b32 s61, 0
	v_add_u32_e32 v141, 0, v16
	v_readlane_b32 s80, v253, 18
	v_readlane_b32 s7, v254, 12
	s_barrier
	s_branch .LBB0_218

.LBB0_240:
	v_bfe_u32 v167, v6, 4, 2
	v_readlane_b32 s40, v254, 43
	v_and_b32_e32 v166, 15, v6
	v_lshlrev_b32_e32 v7, 4, v167
	v_lshlrev_b32_e32 v6, 2, v6
	v_mov_b32_e32 v135, v189
	v_readlane_b32 s41, v254, 44
	s_and_b32 s48, s30, 3
	s_lshl_b32 s60, s11, 6
	v_lshl_or_b32 v7, v166, 6, v7
	s_lshl_b32 s11, s11, 13
	v_and_b32_e32 v6, 32, v6
	v_lshl_add_u64 v[8:9], s[40:41], 0, v[134:135]
	v_mov_b32_e32 v133, v189
	v_readlane_b32 s38, v254, 39
	v_bitop3_b32 v16, v7, s11, v6 bitop3:0xde
	s_lshl_b32 s11, s48, 12
	v_lshl_add_u64 v[10:11], s[40:41], 0, v[132:133]
	v_readlane_b32 s39, v254, 40
	v_bitop3_b32 v168, v7, s11, v6 bitop3:0xde
	s_add_i32 m0, s46, 0x18000
	v_lshl_add_u64 v[6:7], v[8:9], 0, s[62:63]
	v_lshl_add_u64 v[12:13], s[38:39], 0, v[134:135]
	s_lshl_b32 s4, s48, 5
	global_load_lds_dwordx4 v[6:7], off
	v_lshl_add_u64 v[6:7], v[10:11], 0, s[62:63]
	s_add_i32 m0, s46, 0x1a000
	s_add_i32 s56, s46, 0x8000
	v_lshl_add_u64 v[14:15], s[38:39], 0, v[132:133]
	v_writelane_b32 v255, s4, 3
	global_load_lds_dwordx4 v[6:7], off
	v_lshl_add_u64 v[6:7], v[12:13], 0, s[62:63]
	s_mov_b32 m0, s56
	s_add_i32 s57, s46, 0xa000
	v_readlane_b32 s4, v254, 45
	global_load_lds_dwordx4 v[6:7], off
	v_lshl_add_u64 v[6:7], v[14:15], 0, s[62:63]
	s_mov_b32 m0, s57
	v_readlane_b32 s5, v254, 46
	global_load_lds_dwordx4 v[6:7], off
	s_add_i32 m0, s46, 0x1c000
	v_lshl_add_u64 v[6:7], s[4:5], 0, v[134:135]
	global_load_lds_dwordx4 v[6:7], off
	v_lshl_add_u64 v[6:7], s[4:5], 0, v[132:133]
	s_add_i32 m0, s46, 0x1e000
	s_ashr_i32 s20, s10, 31
	global_load_lds_dwordx4 v[6:7], off
	s_waitcnt vmcnt(8)
	s_barrier
	v_lshlrev_b32_e32 v6, 14, v3
	s_lshr_b32 s20, s20, 26
	v_and_b32_e32 v6, 0xffff8000, v6
	s_add_i32 s20, s10, s20
	v_lshl_add_u32 v4, v4, 11, v6
	v_and_b32_e32 v3, 1, v3
	s_ashr_i32 s80, s20, 6
	v_lshl_or_b32 v3, v3, 6, v4
	s_cmp_gt_i32 s10, 63
	v_lshl_add_u32 v136, v5, 1, v3
	v_lshlrev_b32_e32 v3, 14, v0
	s_cselect_b64 s[10:11], -1, 0
	s_add_i32 s49, s80, -2
	v_and_b32_e32 v3, 0xffff8000, v3
	s_waitcnt vmcnt(6)
	s_cmpk_lt_u32 s28, 0x100
	v_lshl_add_u32 v1, v1, 11, v3
	v_and_b32_e32 v0, 1, v0
	v_readlane_b32 s4, v253, 32
	s_cselect_b64 s[86:87], -1, 0
	s_lshl_b32 s20, s48, 6
	v_lshl_or_b32 v0, v0, 6, v1
	v_readlane_b32 s5, v253, 33
	s_bfe_u32 s81, s30, 0x10001
	s_bfe_u32 s88, s28, 0x10006
	v_mov_b32_e32 v137, v189
	v_lshl_add_u32 v138, v2, 1, v0
	v_mov_b32_e32 v139, v189
	s_mov_b32 s89, 0
	v_add_u32_e32 v169, 0, v16
	s_lshl_b32 s28, s20, 1
	v_readlane_b32 s94, v253, 19
	s_mov_b32 s95, s4
	s_movk_i32 s5, 0x1400
	s_barrier
	s_branch .LBB0_243

.LBB0_287:
	v_readlane_b32 s82, v254, 23
	v_mov_b32_e32 v133, v189
	v_readlane_b32 s83, v254, 24
	v_mov_b32_e32 v129, v189
	v_readlane_b32 s66, v254, 19
	v_lshl_add_u64 v[8:9], s[82:83], 0, v[132:133]
	v_lshl_add_u64 v[10:11], s[82:83], 0, v[128:129]
	v_mov_b32_e32 v135, v189
	v_readlane_b32 s67, v254, 20
	s_add_i32 m0, s13, 0x18000
	v_lshl_add_u64 v[8:9], v[8:9], 0, s[62:63]
	v_lshl_add_u64 v[12:13], s[66:67], 0, v[134:135]
	v_mov_b32_e32 v131, v189
	global_load_lds_dwordx4 v[8:9], off
	v_lshl_add_u64 v[8:9], v[10:11], 0, s[62:63]
	s_add_i32 m0, s13, 0x1a000
	s_add_i32 s48, s13, 0x8000
	v_lshl_add_u64 v[14:15], s[66:67], 0, v[130:131]
	global_load_lds_dwordx4 v[8:9], off
	v_lshl_add_u64 v[8:9], v[12:13], 0, s[62:63]
	s_mov_b32 m0, s48
	s_add_i32 s49, s13, 0xa000
	v_readlane_b32 s6, v254, 25
	global_load_lds_dwordx4 v[8:9], off
	v_lshl_add_u64 v[8:9], v[14:15], 0, s[62:63]
	s_mov_b32 m0, s49
	v_readlane_b32 s7, v254, 26
	global_load_lds_dwordx4 v[8:9], off
	s_add_i32 m0, s13, 0x1c000
	v_lshl_add_u64 v[8:9], s[6:7], 0, v[132:133]
	global_load_lds_dwordx4 v[8:9], off
	v_lshl_add_u64 v[8:9], s[6:7], 0, v[128:129]
	s_add_i32 m0, s13, 0x1e000
	s_ashr_i32 s20, s30, 31
	global_load_lds_dwordx4 v[8:9], off
	s_waitcnt vmcnt(8)
	s_barrier
	v_bfe_u32 v150, v1, 4, 2
	s_lshr_b32 s20, s20, 26
	v_and_b32_e32 v149, 15, v1
	s_add_i32 s20, s30, s20
	v_lshlrev_b32_e32 v7, 4, v150
	v_lshlrev_b32_e32 v1, 2, v1
	s_ashr_i32 s55, s20, 6
	v_lshl_or_b32 v7, v149, 6, v7
	s_lshl_b32 s20, s35, 13
	v_and_b32_e32 v1, 32, v1
	v_bitop3_b32 v8, v7, s20, v1 bitop3:0xde
	s_lshl_b32 s20, s31, 5
	s_and_b32 s57, s20, 0x60
	s_lshl_b32 s20, s57, 7
	v_bitop3_b32 v151, v7, s20, v1 bitop3:0xde
	v_lshlrev_b32_e32 v1, 14, v5
	v_and_b32_e32 v1, 0xffff8000, v1
	v_lshl_add_u32 v1, v4, 11, v1
	v_and_b32_e32 v4, 1, v5
	v_lshl_or_b32 v1, v4, 6, v1
	s_lshl_b32 s56, s35, 6
	v_lshl_add_u32 v136, v6, 1, v1
	v_lshlrev_b32_e32 v1, 14, v0
	s_cmp_gt_i32 s30, 63
	v_and_b32_e32 v1, 0xffff8000, v1
	s_waitcnt vmcnt(6)
	s_cselect_b64 s[30:31], -1, 0
	s_add_i32 s60, s55, -2
	v_lshl_add_u32 v1, v2, 11, v1
	v_and_b32_e32 v0, 1, v0
	s_cmpk_lt_u32 s34, 0x100
	v_lshl_or_b32 v0, v0, 6, v1
	v_readlane_b32 s6, v253, 26
	s_cselect_b64 s[34:35], -1, 0
	v_mov_b32_e32 v137, v189
	v_lshl_add_u32 v138, v3, 1, v0
	v_mov_b32_e32 v139, v189
	s_mov_b32 s61, 0
	v_add_u32_e32 v152, 0, v8
	v_readlane_b32 s80, v253, 15
	s_mov_b32 s81, s6
	s_movk_i32 s5, 0xc1
	s_barrier
	v_readlane_b32 s7, v253, 27
	s_branch .LBB0_290

.LBB0_305:
	s_ashr_i32 s20, s30, 31
	v_bfe_u32 v141, v6, 4, 2
	s_lshr_b32 s20, s20, 26
	v_and_b32_e32 v140, 15, v6
	s_add_i32 s20, s30, s20
	v_lshlrev_b32_e32 v7, 4, v141
	v_lshlrev_b32_e32 v6, 2, v6
	s_ashr_i32 s48, s20, 6
	v_lshl_or_b32 v7, v140, 6, v7
	s_lshl_b32 s20, s35, 13
	v_and_b32_e32 v6, 32, v6
	v_readlane_b32 s82, v254, 53
	v_bitop3_b32 v16, v7, s20, v6 bitop3:0xde
	s_lshl_b32 s20, s31, 5
	v_mov_b32_e32 v133, v189
	v_readlane_b32 s83, v254, 54
	s_and_b32 s55, s20, 0x60
	v_mov_b32_e32 v129, v189
	v_lshl_add_u64 v[8:9], s[82:83], 0, v[132:133]
	v_readlane_b32 s66, v254, 49
	s_lshl_b32 s20, s55, 7
	v_lshl_add_u64 v[10:11], s[82:83], 0, v[128:129]
	v_mov_b32_e32 v135, v189
	v_readlane_b32 s67, v254, 50
	v_bitop3_b32 v142, v7, s20, v6 bitop3:0xde
	s_add_i32 m0, s13, 0x18000
	v_lshl_add_u64 v[6:7], v[8:9], 0, s[62:63]
	v_lshl_add_u64 v[12:13], s[66:67], 0, v[134:135]
	v_mov_b32_e32 v131, v189
	global_load_lds_dwordx4 v[6:7], off
	v_lshl_add_u64 v[6:7], v[10:11], 0, s[62:63]
	s_add_i32 m0, s13, 0x1a000
	s_add_i32 s56, s13, 0x8000
	v_lshl_add_u64 v[14:15], s[66:67], 0, v[130:131]
	global_load_lds_dwordx4 v[6:7], off
	v_lshl_add_u64 v[6:7], v[12:13], 0, s[62:63]
	s_mov_b32 m0, s56
	s_add_i32 s57, s13, 0xa000
	v_readlane_b32 s6, v254, 55
	global_load_lds_dwordx4 v[6:7], off
	v_lshl_add_u64 v[6:7], v[14:15], 0, s[62:63]
	s_mov_b32 m0, s57
	v_readlane_b32 s7, v254, 56
	global_load_lds_dwordx4 v[6:7], off
	s_add_i32 m0, s13, 0x1c000
	v_lshl_add_u64 v[6:7], s[6:7], 0, v[132:133]
	global_load_lds_dwordx4 v[6:7], off
	v_lshl_add_u64 v[6:7], s[6:7], 0, v[128:129]
	s_add_i32 m0, s13, 0x1e000
	s_lshl_b32 s49, s35, 6
	global_load_lds_dwordx4 v[6:7], off
	s_waitcnt vmcnt(8)
	s_barrier
	v_lshlrev_b32_e32 v6, 14, v4
	v_and_b32_e32 v6, 0xffff8000, v6
	v_lshl_add_u32 v3, v3, 11, v6
	v_and_b32_e32 v4, 1, v4
	v_lshl_or_b32 v3, v4, 6, v3
	v_lshl_add_u32 v136, v5, 1, v3
	v_lshlrev_b32_e32 v3, 14, v0
	s_cmp_gt_i32 s30, 63
	v_and_b32_e32 v3, 0xffff8000, v3
	s_waitcnt vmcnt(6)
	s_cselect_b64 s[30:31], -1, 0
	s_add_i32 s60, s48, -2
	v_lshl_add_u32 v1, v1, 11, v3
	v_and_b32_e32 v0, 1, v0
	s_cmpk_lt_u32 s34, 0x100
	v_lshl_or_b32 v0, v0, 6, v1
	v_readlane_b32 s6, v253, 49
	s_cselect_b64 s[34:35], -1, 0
	v_mov_b32_e32 v137, v189
	v_lshl_add_u32 v138, v2, 1, v0
	v_mov_b32_e32 v139, v189
	s_mov_b32 s61, 0
	v_add_u32_e32 v143, 0, v16
	v_readlane_b32 s80, v253, 46
	s_mov_b32 s81, s6
	s_barrier
	v_readlane_b32 s7, v253, 50
	s_branch .LBB0_308

.LBB0_567:
	s_and_b32 s80, s31, 3
	v_bfe_u32 v155, v10, 4, 2
	s_ashr_i32 s31, s38, 31
	v_and_b32_e32 v154, 15, v10
	s_lshr_b32 s31, s31, 26
	v_lshlrev_b32_e32 v11, 4, v155
	v_lshlrev_b32_e32 v10, 2, v10
	s_add_i32 s31, s38, s31
	s_lshl_b32 s82, s30, 6
	v_lshl_or_b32 v11, v154, 6, v11
	s_lshl_b32 s30, s30, 13
	v_and_b32_e32 v10, 32, v10
	v_readlane_b32 s44, v251, 22
	s_ashr_i32 s81, s31, 6
	v_bitop3_b32 v16, v11, s30, v10 bitop3:0xde
	s_lshl_b32 s83, s80, 5
	s_lshl_b32 s30, s80, 12
	v_readlane_b32 s16, v254, 13
	v_readlane_b32 s45, v251, 23
	s_cmp_eq_u32 s16, 0
	s_mov_b64 s[36:37], s[44:45]
	v_bitop3_b32 v156, v11, s30, v10 bitop3:0xde
	s_cselect_b32 s31, s37, 0
	s_cselect_b32 s30, s36, 0
	v_readlane_b32 s26, v253, 40
	s_cmp_lg_u64 s[30:31], 0
	v_mov_b32_e32 v141, v189
	v_readlane_b32 s27, v253, 41
	s_cselect_b64 s[34:35], -1, 0
	s_add_i32 m0, s5, 0x18000
	v_lshl_add_u64 v[0:1], v[0:1], 0, s[62:63]
	v_lshl_add_u64 v[12:13], s[26:27], 0, v[140:141]
	v_mov_b32_e32 v139, v189
	global_load_lds_dwordx4 v[0:1], off
	v_lshl_add_u64 v[0:1], v[2:3], 0, s[62:63]
	s_add_i32 m0, s5, 0x1a000
	s_add_i32 s85, s5, 0x8000
	s_add_i32 s86, s5, 0xa000
	v_lshl_add_u64 v[14:15], s[26:27], 0, v[138:139]
	global_load_lds_dwordx4 v[0:1], off
	v_lshl_add_u64 v[0:1], v[12:13], 0, s[62:63]
	s_mov_b32 m0, s85
	s_add_u32 s40, s42, 0x40080
	global_load_lds_dwordx4 v[0:1], off
	v_lshl_add_u64 v[0:1], v[14:15], 0, s[62:63]
	s_mov_b32 m0, s86
	s_addc_u32 s41, s43, 0
	global_load_lds_dwordx4 v[0:1], off
	s_add_i32 m0, s5, 0x1c000
	v_lshl_add_u64 v[0:1], s[40:41], 0, v[188:189]
	global_load_lds_dwordx4 v[0:1], off
	v_lshl_add_u64 v[0:1], s[40:41], 0, v[136:137]
	s_add_i32 m0, s5, 0x1e000
	v_readlane_b32 s17, v254, 14
	global_load_lds_dwordx4 v[0:1], off
	s_waitcnt vmcnt(8)
	s_barrier
	v_lshlrev_b32_e32 v0, 14, v8
	v_and_b32_e32 v0, 0xffff8000, v0
	v_lshl_add_u32 v0, v7, 11, v0
	v_and_b32_e32 v1, 1, v8
	v_lshl_or_b32 v0, v1, 6, v0
	v_lshl_add_u32 v142, v9, 1, v0
	v_lshlrev_b32_e32 v0, 14, v4
	s_cmp_gt_i32 s38, 63
	v_and_b32_e32 v0, 0xffff8000, v0
	s_waitcnt vmcnt(6)
	s_cselect_b64 s[44:45], -1, 0
	s_add_i32 s87, s81, -2
	v_lshl_add_u32 v0, v5, 11, v0
	v_and_b32_e32 v1, 1, v4
	v_readlane_b32 s16, v253, 36
	v_readlane_b32 s46, v251, 24
	v_readlane_b32 s47, v251, 25
	v_readlane_b32 s58, v251, 36
	s_cmpk_lt_u32 s28, 0x100
	v_lshl_or_b32 v0, v1, 6, v0
	v_readlane_b32 s17, v253, 37
	s_mov_b32 s84, 0
	v_readlane_b32 s48, v251, 26
	v_readlane_b32 s50, v251, 28
	s_cselect_b64 s[46:47], -1, 0
	v_mov_b32_e32 v143, v189
	v_lshl_add_u32 v144, v6, 1, v0
	v_mov_b32_e32 v145, v189
	v_add_u32_e32 v157, 0, v16
	v_readlane_b32 s28, v253, 18
	s_mov_b32 s58, s16
	s_mov_b64 s[40:41], s[26:27]
	s_movk_i32 s9, 0x60
	s_mov_b64 s[16:17], s[64:65]
	v_readlane_b32 s49, v251, 27
	v_readlane_b32 s51, v251, 29
	v_readlane_b32 s52, v251, 30
	v_readlane_b32 s53, v251, 31
	v_readlane_b32 s54, v251, 32
	v_readlane_b32 s55, v251, 33
	v_readlane_b32 s56, v251, 34
	v_readlane_b32 s57, v251, 35
	v_readlane_b32 s59, v251, 37
	s_barrier
	s_branch .LBB0_570

.LBB0_723:
	s_and_b32 s59, s21, 3
	v_bfe_u32 v149, v14, 4, 2
	s_ashr_i32 s21, s30, 31
	v_and_b32_e32 v148, 15, v14
	s_lshr_b32 s21, s21, 26
	v_lshlrev_b32_e32 v15, 4, v149
	v_lshlrev_b32_e32 v14, 2, v14
	s_add_i32 s21, s30, s21
	s_lshl_b32 s61, s20, 6
	v_lshl_or_b32 v15, v148, 6, v15
	s_lshl_b32 s20, s20, 13
	v_and_b32_e32 v14, 32, v14
	s_ashr_i32 s60, s21, 6
	v_bitop3_b32 v16, v15, s20, v14 bitop3:0xde
	s_lshl_b32 s66, s59, 5
	s_lshl_b32 s20, s59, 12
	v_bitop3_b32 v150, v15, s20, v14 bitop3:0xde
	s_add_u32 s20, s96, 0x400000
	s_addc_u32 s21, s97, 0
	s_add_i32 m0, s55, 0x18000
	v_lshl_add_u64 v[6:7], v[6:7], 0, s[62:63]
	global_load_lds_dwordx4 v[6:7], off
	v_lshl_add_u64 v[4:5], v[4:5], 0, s[62:63]
	s_add_i32 m0, s55, 0x1a000
	s_add_i32 s67, s55, 0x8000
	s_add_i32 s69, s55, 0xa000
	global_load_lds_dwordx4 v[4:5], off
	v_lshl_add_u64 v[0:1], v[0:1], 0, s[62:63]
	s_mov_b32 m0, s67
	s_add_u32 s34, s48, 0x40080
	global_load_lds_dwordx4 v[0:1], off
	v_lshl_add_u64 v[0:1], v[2:3], 0, s[62:63]
	s_mov_b32 m0, s69
	s_addc_u32 s35, s49, 0
	global_load_lds_dwordx4 v[0:1], off
	s_add_i32 m0, s55, 0x1c000
	v_lshl_add_u64 v[0:1], s[34:35], 0, v[188:189]
	global_load_lds_dwordx4 v[0:1], off
	v_lshl_add_u64 v[0:1], s[34:35], 0, v[128:129]
	s_add_i32 m0, s55, 0x1e000
	s_cmp_gt_i32 s30, 63
	global_load_lds_dwordx4 v[0:1], off
	s_waitcnt vmcnt(8)
	s_barrier
	v_lshlrev_b32_e32 v0, 14, v12
	v_and_b32_e32 v0, 0xffff8000, v0
	v_lshl_add_u32 v0, v11, 11, v0
	v_and_b32_e32 v1, 1, v12
	v_lshl_or_b32 v0, v1, 6, v0
	v_lshl_add_u32 v134, v13, 1, v0
	v_lshlrev_b32_e32 v0, 14, v8
	v_and_b32_e32 v0, 0xffff8000, v0
	v_readlane_b32 s6, v253, 36
	s_waitcnt vmcnt(6)
	s_cselect_b64 s[30:31], -1, 0
	s_add_i32 s70, s60, -2
	v_lshl_add_u32 v0, v9, 11, v0
	v_and_b32_e32 v1, 1, v8
	v_readlane_b32 s7, v253, 37
	s_cmpk_lt_u32 s28, 0x100
	v_lshl_or_b32 v0, v1, 6, v0
	s_mov_b32 s80, s6
	v_readlane_b32 s6, v254, 11
	s_cselect_b64 s[34:35], -1, 0
	v_mov_b32_e32 v135, v189
	v_lshl_add_u32 v136, v10, 1, v0
	v_mov_b32_e32 v137, v189
	s_mov_b32 s71, 0
	v_add_u32_e32 v151, 0, v16
	v_readlane_b32 s28, v253, 18
	v_readlane_b32 s7, v254, 12
	s_barrier
	v_readlane_b32 s5, v254, 5
	s_branch .LBB0_726
